# removed the redundant second accumulator-zeroing block in front of six GEMM main loops; residual GEMM prologue issues both K-tile DMA batches up front
# speedup vs baseline: 1.0146x; 1.0100x over previous
.LBB0_1085:
	v_mov_b32_e32 v121, 0
	s_andn2_b64 vcc, exec, s[14:15]
	v_mov_b32_e32 v120, v121
	v_mov_b32_e32 v119, v121
	v_mov_b32_e32 v118, v121
	v_mov_b32_e32 v117, v121
	v_mov_b32_e32 v116, v121
	v_mov_b32_e32 v115, v121
	v_mov_b32_e32 v114, v121
	v_mov_b32_e32 v105, v121
	v_mov_b32_e32 v104, v121
	v_mov_b32_e32 v103, v121
	v_mov_b32_e32 v102, v121
	v_mov_b32_e32 v101, v121
	v_mov_b32_e32 v100, v121
	v_mov_b32_e32 v99, v121
	v_mov_b32_e32 v98, v121
	s_waitcnt vmcnt(0)
	v_mov_b32_e32 v89, v121
	v_mov_b32_e32 v88, v121
	v_mov_b32_e32 v87, v121
	v_mov_b32_e32 v86, v121
	v_mov_b32_e32 v85, v121
	v_mov_b32_e32 v84, v121
	v_mov_b32_e32 v83, v121
	v_mov_b32_e32 v82, v121
	v_mov_b32_e32 v73, v121
	v_mov_b32_e32 v72, v121
	v_mov_b32_e32 v71, v121
	v_mov_b32_e32 v70, v121
	v_mov_b32_e32 v69, v121
	v_mov_b32_e32 v68, v121
	v_mov_b32_e32 v67, v121
	v_mov_b32_e32 v66, v121
	v_mov_b32_e32 v129, v121
	v_mov_b32_e32 v128, v121
	v_mov_b32_e32 v127, v121
	v_mov_b32_e32 v126, v121
	v_mov_b32_e32 v125, v121
	v_mov_b32_e32 v124, v121
	v_mov_b32_e32 v123, v121
	v_mov_b32_e32 v122, v121
	v_mov_b32_e32 v113, v121
	v_mov_b32_e32 v112, v121
	v_mov_b32_e32 v111, v121
	v_mov_b32_e32 v110, v121
	v_mov_b32_e32 v109, v121
	v_mov_b32_e32 v108, v121
	v_mov_b32_e32 v107, v121
	v_mov_b32_e32 v106, v121
	v_mov_b32_e32 v97, v121
	v_mov_b32_e32 v96, v121
	v_mov_b32_e32 v95, v121
	v_mov_b32_e32 v94, v121
	v_mov_b32_e32 v93, v121
	v_mov_b32_e32 v92, v121
	v_mov_b32_e32 v91, v121
	v_mov_b32_e32 v90, v121
	v_mov_b32_e32 v81, v121
	v_mov_b32_e32 v80, v121
	v_mov_b32_e32 v79, v121
	v_mov_b32_e32 v78, v121
	v_mov_b32_e32 v77, v121
	v_mov_b32_e32 v76, v121
	v_mov_b32_e32 v75, v121
	v_mov_b32_e32 v74, v121
	v_mov_b32_e32 v57, v121
	v_mov_b32_e32 v56, v121
	v_mov_b32_e32 v55, v121
	v_mov_b32_e32 v54, v121
	v_mov_b32_e32 v53, v121
	v_mov_b32_e32 v52, v121
	v_mov_b32_e32 v51, v121
	v_mov_b32_e32 v50, v121
	v_mov_b32_e32 v41, v121
	v_mov_b32_e32 v40, v121
	v_mov_b32_e32 v39, v121
	v_mov_b32_e32 v38, v121
	v_mov_b32_e32 v37, v121
	v_mov_b32_e32 v36, v121
	v_mov_b32_e32 v35, v121
	v_mov_b32_e32 v34, v121
	v_mov_b32_e32 v25, v121
	v_mov_b32_e32 v24, v121
	v_mov_b32_e32 v23, v121
	v_mov_b32_e32 v22, v121
	v_mov_b32_e32 v21, v121
	v_mov_b32_e32 v20, v121
	v_mov_b32_e32 v19, v121
	v_mov_b32_e32 v18, v121
	v_mov_b32_e32 v9, v121
	v_mov_b32_e32 v8, v121
	v_mov_b32_e32 v7, v121
	v_mov_b32_e32 v6, v121
	v_mov_b32_e32 v5, v121
	v_mov_b32_e32 v4, v121
	v_mov_b32_e32 v3, v121
	v_mov_b32_e32 v2, v121
	v_mov_b32_e32 v65, v121
	v_mov_b32_e32 v64, v121
	v_mov_b32_e32 v63, v121
	v_mov_b32_e32 v62, v121
	v_mov_b32_e32 v61, v121
	v_mov_b32_e32 v60, v121
	v_mov_b32_e32 v59, v121
	v_mov_b32_e32 v58, v121
	v_mov_b32_e32 v49, v121
	v_mov_b32_e32 v48, v121
	v_mov_b32_e32 v47, v121
	v_mov_b32_e32 v46, v121
	v_mov_b32_e32 v45, v121
	v_mov_b32_e32 v44, v121
	v_mov_b32_e32 v43, v121
	v_mov_b32_e32 v42, v121
	v_mov_b32_e32 v33, v121
	v_mov_b32_e32 v32, v121
	v_mov_b32_e32 v31, v121
	v_mov_b32_e32 v30, v121
	v_mov_b32_e32 v29, v121
	v_mov_b32_e32 v28, v121
	v_mov_b32_e32 v27, v121
	v_mov_b32_e32 v26, v121
	v_mov_b32_e32 v17, v121
	v_mov_b32_e32 v16, v121
	v_mov_b32_e32 v15, v121
	v_mov_b32_e32 v14, v121
	v_mov_b32_e32 v13, v121
	v_mov_b32_e32 v12, v121
	v_mov_b32_e32 v11, v121
	v_mov_b32_e32 v10, v121
	s_cbranch_vccnz .LBB0_1089
	s_add_u32 s20, s20, 0x80
	s_addc_u32 s21, s21, 0
	s_add_u32 s44, s22, 0x100
	s_addc_u32 s46, s23, 0
	s_mov_b32 s22, 0

.LBB0_1177:
	v_mov_b32_e32 v129, 0
	s_andn2_b64 vcc, exec, s[18:19]
	v_mov_b32_e32 v128, v129
	v_mov_b32_e32 v127, v129
	v_mov_b32_e32 v126, v129
	v_mov_b32_e32 v125, v129
	v_mov_b32_e32 v124, v129
	v_mov_b32_e32 v123, v129
	v_mov_b32_e32 v122, v129
	v_mov_b32_e32 v113, v129
	v_mov_b32_e32 v112, v129
	v_mov_b32_e32 v111, v129
	v_mov_b32_e32 v110, v129
	v_mov_b32_e32 v109, v129
	v_mov_b32_e32 v108, v129
	v_mov_b32_e32 v107, v129
	v_mov_b32_e32 v106, v129
	v_mov_b32_e32 v97, v129
	v_mov_b32_e32 v96, v129
	v_mov_b32_e32 v95, v129
	v_mov_b32_e32 v94, v129
	v_mov_b32_e32 v93, v129
	v_mov_b32_e32 v92, v129
	v_mov_b32_e32 v91, v129
	v_mov_b32_e32 v90, v129
	v_mov_b32_e32 v81, v129
	v_mov_b32_e32 v80, v129
	v_mov_b32_e32 v79, v129
	v_mov_b32_e32 v78, v129
	v_mov_b32_e32 v77, v129
	v_mov_b32_e32 v76, v129
	v_mov_b32_e32 v75, v129
	v_mov_b32_e32 v74, v129
	v_mov_b32_e32 v121, v129
	v_mov_b32_e32 v120, v129
	v_mov_b32_e32 v119, v129
	v_mov_b32_e32 v118, v129
	v_mov_b32_e32 v117, v129
	v_mov_b32_e32 v116, v129
	v_mov_b32_e32 v115, v129
	v_mov_b32_e32 v114, v129
	v_mov_b32_e32 v105, v129
	v_mov_b32_e32 v104, v129
	v_mov_b32_e32 v103, v129
	v_mov_b32_e32 v102, v129
	v_mov_b32_e32 v101, v129
	v_mov_b32_e32 v100, v129
	v_mov_b32_e32 v99, v129
	v_mov_b32_e32 v98, v129
	s_waitcnt vmcnt(0)
	v_mov_b32_e32 v89, v129
	v_mov_b32_e32 v88, v129
	v_mov_b32_e32 v87, v129
	v_mov_b32_e32 v86, v129
	v_mov_b32_e32 v85, v129
	v_mov_b32_e32 v84, v129
	v_mov_b32_e32 v83, v129
	v_mov_b32_e32 v82, v129
	v_mov_b32_e32 v73, v129
	v_mov_b32_e32 v72, v129
	v_mov_b32_e32 v71, v129
	v_mov_b32_e32 v70, v129
	v_mov_b32_e32 v69, v129
	v_mov_b32_e32 v68, v129
	v_mov_b32_e32 v67, v129
	v_mov_b32_e32 v66, v129
	v_mov_b32_e32 v65, v129
	v_mov_b32_e32 v64, v129
	v_mov_b32_e32 v63, v129
	v_mov_b32_e32 v62, v129
	v_mov_b32_e32 v61, v129
	v_mov_b32_e32 v60, v129
	v_mov_b32_e32 v59, v129
	v_mov_b32_e32 v58, v129
	v_mov_b32_e32 v49, v129
	v_mov_b32_e32 v48, v129
	v_mov_b32_e32 v47, v129
	v_mov_b32_e32 v46, v129
	v_mov_b32_e32 v45, v129
	v_mov_b32_e32 v44, v129
	v_mov_b32_e32 v43, v129
	v_mov_b32_e32 v42, v129
	v_mov_b32_e32 v33, v129
	v_mov_b32_e32 v32, v129
	v_mov_b32_e32 v31, v129
	v_mov_b32_e32 v30, v129
	v_mov_b32_e32 v29, v129
	v_mov_b32_e32 v28, v129
	v_mov_b32_e32 v27, v129
	v_mov_b32_e32 v26, v129
	v_mov_b32_e32 v17, v129
	v_mov_b32_e32 v16, v129
	v_mov_b32_e32 v15, v129
	v_mov_b32_e32 v14, v129
	v_mov_b32_e32 v13, v129
	v_mov_b32_e32 v12, v129
	v_mov_b32_e32 v11, v129
	v_mov_b32_e32 v10, v129
	v_mov_b32_e32 v57, v129
	v_mov_b32_e32 v56, v129
	v_mov_b32_e32 v55, v129
	v_mov_b32_e32 v54, v129
	v_mov_b32_e32 v53, v129
	v_mov_b32_e32 v52, v129
	v_mov_b32_e32 v51, v129
	v_mov_b32_e32 v50, v129
	v_mov_b32_e32 v41, v129
	v_mov_b32_e32 v40, v129
	v_mov_b32_e32 v39, v129
	v_mov_b32_e32 v38, v129
	v_mov_b32_e32 v37, v129
	v_mov_b32_e32 v36, v129
	v_mov_b32_e32 v35, v129
	v_mov_b32_e32 v34, v129
	v_mov_b32_e32 v25, v129
	v_mov_b32_e32 v24, v129
	v_mov_b32_e32 v23, v129
	v_mov_b32_e32 v22, v129
	v_mov_b32_e32 v21, v129
	v_mov_b32_e32 v20, v129
	v_mov_b32_e32 v19, v129
	v_mov_b32_e32 v18, v129
	v_mov_b32_e32 v9, v129
	v_mov_b32_e32 v8, v129
	v_mov_b32_e32 v7, v129
	v_mov_b32_e32 v6, v129
	v_mov_b32_e32 v5, v129
	v_mov_b32_e32 v4, v129
	v_mov_b32_e32 v3, v129
	v_mov_b32_e32 v2, v129
	s_cbranch_vccnz .LBB0_1181
	s_add_u32 s61, s28, 0x100
	s_waitcnt lgkmcnt(0)
	s_addc_u32 s62, s29, 0
	s_mov_b32 s34, 0
	s_mov_b64 s[28:29], 0

.LBB0_1233:
	v_mov_b32_e32 v125, 0
	s_andn2_b64 vcc, exec, s[16:17]
	v_mov_b32_e32 v124, v125
	v_mov_b32_e32 v123, v125
	v_mov_b32_e32 v122, v125
	v_mov_b32_e32 v129, v125
	v_mov_b32_e32 v128, v125
	v_mov_b32_e32 v127, v125
	v_mov_b32_e32 v126, v125
	v_mov_b32_e32 v113, v125
	v_mov_b32_e32 v112, v125
	v_mov_b32_e32 v111, v125
	v_mov_b32_e32 v110, v125
	v_mov_b32_e32 v109, v125
	v_mov_b32_e32 v108, v125
	v_mov_b32_e32 v107, v125
	v_mov_b32_e32 v106, v125
	v_mov_b32_e32 v97, v125
	v_mov_b32_e32 v96, v125
	v_mov_b32_e32 v95, v125
	v_mov_b32_e32 v94, v125
	v_mov_b32_e32 v93, v125
	v_mov_b32_e32 v92, v125
	v_mov_b32_e32 v91, v125
	v_mov_b32_e32 v90, v125
	v_mov_b32_e32 v81, v125
	v_mov_b32_e32 v80, v125
	v_mov_b32_e32 v79, v125
	v_mov_b32_e32 v78, v125
	v_mov_b32_e32 v77, v125
	v_mov_b32_e32 v76, v125
	v_mov_b32_e32 v75, v125
	v_mov_b32_e32 v74, v125
	v_mov_b32_e32 v121, v125
	v_mov_b32_e32 v120, v125
	v_mov_b32_e32 v119, v125
	v_mov_b32_e32 v118, v125
	v_mov_b32_e32 v117, v125
	v_mov_b32_e32 v116, v125
	v_mov_b32_e32 v115, v125
	v_mov_b32_e32 v114, v125
	v_mov_b32_e32 v105, v125
	v_mov_b32_e32 v104, v125
	v_mov_b32_e32 v103, v125
	v_mov_b32_e32 v102, v125
	v_mov_b32_e32 v101, v125
	v_mov_b32_e32 v100, v125
	v_mov_b32_e32 v99, v125
	v_mov_b32_e32 v98, v125
	s_waitcnt vmcnt(0)
	v_mov_b32_e32 v89, v125
	v_mov_b32_e32 v88, v125
	v_mov_b32_e32 v87, v125
	v_mov_b32_e32 v86, v125
	v_mov_b32_e32 v85, v125
	v_mov_b32_e32 v84, v125
	v_mov_b32_e32 v83, v125
	v_mov_b32_e32 v82, v125
	v_mov_b32_e32 v73, v125
	v_mov_b32_e32 v72, v125
	v_mov_b32_e32 v71, v125
	v_mov_b32_e32 v70, v125
	v_mov_b32_e32 v69, v125
	v_mov_b32_e32 v68, v125
	v_mov_b32_e32 v67, v125
	v_mov_b32_e32 v66, v125
	v_mov_b32_e32 v65, v125
	v_mov_b32_e32 v64, v125
	v_mov_b32_e32 v63, v125
	v_mov_b32_e32 v62, v125
	v_mov_b32_e32 v61, v125
	v_mov_b32_e32 v60, v125
	v_mov_b32_e32 v59, v125
	v_mov_b32_e32 v58, v125
	v_mov_b32_e32 v49, v125
	v_mov_b32_e32 v48, v125
	v_mov_b32_e32 v47, v125
	v_mov_b32_e32 v46, v125
	v_mov_b32_e32 v45, v125
	v_mov_b32_e32 v44, v125
	v_mov_b32_e32 v43, v125
	v_mov_b32_e32 v42, v125
	v_mov_b32_e32 v33, v125
	v_mov_b32_e32 v32, v125
	v_mov_b32_e32 v31, v125
	v_mov_b32_e32 v30, v125
	v_mov_b32_e32 v29, v125
	v_mov_b32_e32 v28, v125
	v_mov_b32_e32 v27, v125
	v_mov_b32_e32 v26, v125
	v_mov_b32_e32 v17, v125
	v_mov_b32_e32 v16, v125
	v_mov_b32_e32 v15, v125
	v_mov_b32_e32 v14, v125
	v_mov_b32_e32 v13, v125
	v_mov_b32_e32 v12, v125
	v_mov_b32_e32 v11, v125
	v_mov_b32_e32 v10, v125
	v_mov_b32_e32 v57, v125
	v_mov_b32_e32 v56, v125
	v_mov_b32_e32 v55, v125
	v_mov_b32_e32 v54, v125
	v_mov_b32_e32 v53, v125
	v_mov_b32_e32 v52, v125
	v_mov_b32_e32 v51, v125
	v_mov_b32_e32 v50, v125
	v_mov_b32_e32 v41, v125
	v_mov_b32_e32 v40, v125
	v_mov_b32_e32 v39, v125
	v_mov_b32_e32 v38, v125
	v_mov_b32_e32 v37, v125
	v_mov_b32_e32 v36, v125
	v_mov_b32_e32 v35, v125
	v_mov_b32_e32 v34, v125
	v_mov_b32_e32 v25, v125
	v_mov_b32_e32 v24, v125
	v_mov_b32_e32 v23, v125
	v_mov_b32_e32 v22, v125
	v_mov_b32_e32 v21, v125
	v_mov_b32_e32 v20, v125
	v_mov_b32_e32 v19, v125
	v_mov_b32_e32 v18, v125
	v_mov_b32_e32 v9, v125
	v_mov_b32_e32 v8, v125
	v_mov_b32_e32 v7, v125
	v_mov_b32_e32 v6, v125
	v_mov_b32_e32 v5, v125
	v_mov_b32_e32 v4, v125
	v_mov_b32_e32 v3, v125
	v_mov_b32_e32 v2, v125
	s_cbranch_vccnz .LBB0_1237
	s_add_u32 s0, s0, 0x80
	s_addc_u32 s1, s1, 0
	s_add_u32 s24, s24, 0x100
	s_addc_u32 s25, s25, 0
	s_mov_b32 s4, 0

.LBB0_1577:
	v_mov_b32_e32 v125, 0
	s_andn2_b64 vcc, exec, s[12:13]
	v_mov_b32_e32 v124, v125
	v_mov_b32_e32 v123, v125
	v_mov_b32_e32 v122, v125
	v_mov_b32_e32 v129, v125
	v_mov_b32_e32 v128, v125
	v_mov_b32_e32 v127, v125
	v_mov_b32_e32 v126, v125
	v_mov_b32_e32 v113, v125
	v_mov_b32_e32 v112, v125
	v_mov_b32_e32 v111, v125
	v_mov_b32_e32 v110, v125
	v_mov_b32_e32 v109, v125
	v_mov_b32_e32 v108, v125
	v_mov_b32_e32 v107, v125
	v_mov_b32_e32 v106, v125
	v_mov_b32_e32 v97, v125
	v_mov_b32_e32 v96, v125
	v_mov_b32_e32 v95, v125
	v_mov_b32_e32 v94, v125
	v_mov_b32_e32 v93, v125
	v_mov_b32_e32 v92, v125
	v_mov_b32_e32 v91, v125
	v_mov_b32_e32 v90, v125
	v_mov_b32_e32 v81, v125
	v_mov_b32_e32 v80, v125
	v_mov_b32_e32 v79, v125
	v_mov_b32_e32 v78, v125
	v_mov_b32_e32 v77, v125
	v_mov_b32_e32 v76, v125
	v_mov_b32_e32 v75, v125
	v_mov_b32_e32 v74, v125
	v_mov_b32_e32 v121, v125
	v_mov_b32_e32 v120, v125
	v_mov_b32_e32 v119, v125
	v_mov_b32_e32 v118, v125
	v_mov_b32_e32 v117, v125
	v_mov_b32_e32 v116, v125
	v_mov_b32_e32 v115, v125
	v_mov_b32_e32 v114, v125
	v_mov_b32_e32 v105, v125
	v_mov_b32_e32 v104, v125
	v_mov_b32_e32 v103, v125
	v_mov_b32_e32 v102, v125
	v_mov_b32_e32 v101, v125
	v_mov_b32_e32 v100, v125
	v_mov_b32_e32 v99, v125
	v_mov_b32_e32 v98, v125
	s_waitcnt vmcnt(0)
	v_mov_b32_e32 v89, v125
	v_mov_b32_e32 v88, v125
	v_mov_b32_e32 v87, v125
	v_mov_b32_e32 v86, v125
	v_mov_b32_e32 v85, v125
	v_mov_b32_e32 v84, v125
	v_mov_b32_e32 v83, v125
	v_mov_b32_e32 v82, v125
	v_mov_b32_e32 v73, v125
	v_mov_b32_e32 v72, v125
	v_mov_b32_e32 v71, v125
	v_mov_b32_e32 v70, v125
	v_mov_b32_e32 v69, v125
	v_mov_b32_e32 v68, v125
	v_mov_b32_e32 v67, v125
	v_mov_b32_e32 v66, v125
	v_mov_b32_e32 v65, v125
	v_mov_b32_e32 v64, v125
	v_mov_b32_e32 v63, v125
	v_mov_b32_e32 v62, v125
	v_mov_b32_e32 v61, v125
	v_mov_b32_e32 v60, v125
	v_mov_b32_e32 v59, v125
	v_mov_b32_e32 v58, v125
	v_mov_b32_e32 v49, v125
	v_mov_b32_e32 v48, v125
	v_mov_b32_e32 v47, v125
	v_mov_b32_e32 v46, v125
	v_mov_b32_e32 v45, v125
	v_mov_b32_e32 v44, v125
	v_mov_b32_e32 v43, v125
	v_mov_b32_e32 v42, v125
	v_mov_b32_e32 v33, v125
	v_mov_b32_e32 v32, v125
	v_mov_b32_e32 v31, v125
	v_mov_b32_e32 v30, v125
	v_mov_b32_e32 v29, v125
	v_mov_b32_e32 v28, v125
	v_mov_b32_e32 v27, v125
	v_mov_b32_e32 v26, v125
	v_mov_b32_e32 v17, v125
	v_mov_b32_e32 v16, v125
	v_mov_b32_e32 v15, v125
	v_mov_b32_e32 v14, v125
	v_mov_b32_e32 v13, v125
	v_mov_b32_e32 v12, v125
	v_mov_b32_e32 v11, v125
	v_mov_b32_e32 v10, v125
	v_mov_b32_e32 v57, v125
	v_mov_b32_e32 v56, v125
	v_mov_b32_e32 v55, v125
	v_mov_b32_e32 v54, v125
	v_mov_b32_e32 v53, v125
	v_mov_b32_e32 v52, v125
	v_mov_b32_e32 v51, v125
	v_mov_b32_e32 v50, v125
	v_mov_b32_e32 v41, v125
	v_mov_b32_e32 v40, v125
	v_mov_b32_e32 v39, v125
	v_mov_b32_e32 v38, v125
	v_mov_b32_e32 v37, v125
	v_mov_b32_e32 v36, v125
	v_mov_b32_e32 v35, v125
	v_mov_b32_e32 v34, v125
	v_mov_b32_e32 v25, v125
	v_mov_b32_e32 v24, v125
	v_mov_b32_e32 v23, v125
	v_mov_b32_e32 v22, v125
	v_mov_b32_e32 v21, v125
	v_mov_b32_e32 v20, v125
	v_mov_b32_e32 v19, v125
	v_mov_b32_e32 v18, v125
	v_mov_b32_e32 v9, v125
	v_mov_b32_e32 v8, v125
	v_mov_b32_e32 v7, v125
	v_mov_b32_e32 v6, v125
	v_mov_b32_e32 v5, v125
	v_mov_b32_e32 v4, v125
	v_mov_b32_e32 v3, v125
	v_mov_b32_e32 v2, v125
	s_cbranch_vccnz .LBB0_1580
	s_add_u32 s0, s0, 0x80
	s_addc_u32 s1, s1, 0
	s_add_u32 s37, s18, 0x100
	s_addc_u32 s38, s19, 0
	s_mov_b32 s18, 0

.LBB0_1592:
	s_and_b64 vcc, exec, s[2:3]
	s_cbranch_vccnz .LBB0_1634
	v_bfe_i32 v3, v14, 27, 1
	v_lshlrev_b32_e32 v2, 4, v14
	v_lshrrev_b32_e32 v3, 22, v3
	v_add_u32_e32 v3, v2, v3
	v_and_b32_e32 v3, 0xfffffc00, v3
	v_ashrrev_i32_e32 v0, 31, v14
	v_sub_u32_e32 v3, v2, v3
	v_lshrrev_b32_e32 v0, 26, v0
	v_lshrrev_b32_e32 v4, 4, v3
	v_add_u32_e32 v0, v14, v0
	v_bitop3_b32 v4, v4, v3, 32 bitop3:0x6c
	v_ashrrev_i32_e32 v3, 31, v3
	v_readlane_b32 s0, v254, 5
	v_ashrrev_i32_e32 v0, 6, v0
	v_lshrrev_b32_e32 v3, 26, v3
	s_add_u32 s2, s0, 0xb00000
	v_readlane_b32 s0, v254, 13
	v_lshlrev_b32_e32 v5, 3, v0
	v_add_u32_e32 v3, v4, v3
	s_addc_u32 s3, s0, 0
	v_readlane_b32 s0, v254, 43
	v_and_b32_e32 v5, -16, v5
	v_ashrrev_i32_e32 v3, 6, v3
	v_lshlrev_b32_e32 v0, 5, v0
	v_readlane_b32 s1, v254, 44
	s_add_u32 s0, s64, s0
	v_readlane_b32 s5, v255, 11
	v_add_u32_e32 v5, v3, v5
	v_and_b32_e32 v15, 32, v0
	v_mul_i32_i24_e32 v0, 64, v3
	s_addc_u32 s1, s65, s1
	s_lshl_b32 s5, s5, 1
	v_sub_u32_e32 v0, v4, v0
	v_lshlrev_b32_e32 v4, 1, v5
	v_lshrrev_b32_e32 v6, 2, v5
	v_and_b32_e32 v3, 3, v3
	s_add_u32 s5, s0, s5
	v_readlane_b32 s12, v254, 29
	v_ashrrev_i16_sdwa v0, v188, sext(v0) dst_sel:DWORD dst_unused:UNUSED_PAD src0_sel:DWORD src1_sel:BYTE_0
	v_and_b32_e32 v4, 24, v4
	v_and_b32_e32 v6, 4, v6
	v_and_or_b32 v3, v5, s74, v3
	s_addc_u32 s7, s1, 0
	v_readlane_b32 s13, v254, 30
	v_bfe_i32 v16, v0, 0, 16
	v_or3_b32 v3, v3, v6, v4
	s_and_b64 s[0:1], s[12:13], exec
	v_add_u32_e32 v0, v15, v16
	v_mul_lo_u32 v17, v5, s4
	v_mul_lo_u32 v3, v3, s4
	v_add_u32_e32 v2, 0x2000, v2
	s_cselect_b32 s22, s3, s7
	s_cselect_b32 s23, s2, s5
	s_ashr_i32 s2, s6, 6
	v_add_lshl_u32 v142, v0, v17, 1
	v_add_lshl_u32 v0, v3, v0, 1
	v_ashrrev_i32_e32 v3, 31, v2
	s_ashr_i32 s5, s4, 31
	v_lshrrev_b32_e32 v3, 22, v3
	s_ashr_i32 s3, s6, 8
	s_lshl_b64 s[8:9], s[4:5], 8
	s_lshl_b64 s[10:11], s[4:5], 9
	s_lshl_b32 s24, s2, 10
	v_add_u32_e32 v3, v2, v3
	s_and_b64 s[0:1], s[12:13], exec
	v_ashrrev_i32_e32 v3, 10, v3
	v_readlane_b32 s0, v254, 7
	v_mul_i32_i24_e32 v4, 0x400, v3
	v_readlane_b32 s1, v254, 8
	v_sub_u32_e32 v2, v2, v4
	s_cselect_b32 s25, s51, s1
	s_cselect_b32 s26, s50, s0
	s_ashr_i32 s0, s41, 31
	v_lshrrev_b32_e32 v4, 4, v2
	s_mul_i32 s0, s10, s0
	s_mul_hi_u32 s1, s10, s41
	v_bitop3_b32 v2, v4, v2, 32 bitop3:0x6c
	s_add_i32 s7, s1, s0
	s_lshr_b64 s[0:1], s[4:5], 23
	v_ashrrev_i32_e32 v5, 31, v2
	s_mul_i32 s1, s0, s41
	v_lshrrev_b32_e32 v5, 26, v5
	s_add_i32 s7, s7, s1
	s_ashr_i32 s1, s33, 31
	v_lshlrev_b32_e32 v4, 3, v3
	v_add_u32_e32 v5, v2, v5
	s_mul_i32 s1, s10, s1
	s_mul_hi_u32 s13, s10, s33
	v_and_b32_e32 v4, -16, v4
	v_ashrrev_i32_e32 v6, 6, v5
	v_lshlrev_b32_e32 v3, 5, v3
	s_add_i32 s1, s13, s1
	s_mul_i32 s0, s0, s33
	v_add_u32_e32 v4, v6, v4
	v_and_b32_e32 v18, 32, v3
	v_and_b32_e32 v3, 0xc0, v5
	s_add_i32 s1, s1, s0
	s_mul_i32 s0, s10, s33
	v_sub_u32_e32 v2, v2, v3
	v_lshlrev_b32_e32 v3, 1, v4
	v_lshrrev_b32_e32 v5, 2, v4
	v_and_b32_e32 v6, 3, v6
	s_add_u32 s20, s23, s0
	v_ashrrev_i16_sdwa v2, v188, sext(v2) dst_sel:DWORD dst_unused:UNUSED_PAD src0_sel:DWORD src1_sel:BYTE_0
	v_and_b32_e32 v3, 24, v3
	v_and_b32_e32 v5, 4, v5
	v_and_or_b32 v6, v4, s74, v6
	s_addc_u32 s21, s22, s1
	s_add_i32 s27, s24, 0
	v_bfe_i32 v19, v2, 0, 16
	v_or3_b32 v3, v6, v5, v3
	s_add_i32 m0, s27, 0x10000
	v_add_u32_e32 v2, v18, v19
	v_mul_lo_u32 v3, v3, s4
	global_load_lds_dwordx4 v0, s[20:21]
	s_add_i32 m0, s27, 0x12000
	v_add_lshl_u32 v146, v3, v2, 1
	s_add_u32 s0, s20, s8
	global_load_lds_dwordx4 v146, s[20:21]
	s_addc_u32 s1, s21, s9
	s_add_i32 m0, s27, 0x14000
	s_mul_i32 s12, s10, s41
	v_mov_b32_e32 v147, v1
	global_load_lds_dwordx4 v0, s[0:1]
	s_add_i32 m0, s27, 0x16000
	v_lshl_add_u64 v[6:7], s[0:1], 0, v[0:1]
	v_lshl_add_u64 v[8:9], s[0:1], 0, v[146:147]
	global_load_lds_dwordx4 v146, s[0:1]
	s_add_u32 s0, s26, s12
	s_addc_u32 s1, s25, s7
	s_add_i32 s28, s27, 0x2000
	v_mul_lo_u32 v20, v4, s4
	s_mov_b32 m0, s27
	s_add_u32 s12, s0, s8
	v_add_lshl_u32 v144, v2, v20, 1
	global_load_lds_dwordx4 v142, s[0:1]
	s_mov_b32 m0, s28
	s_addc_u32 s13, s1, s9
	s_add_i32 s29, s27, 0x4000
	global_load_lds_dwordx4 v144, s[0:1]
	s_mov_b32 m0, s29
	s_add_i32 s30, s27, 0x6000
	global_load_lds_dwordx4 v142, s[12:13]
	s_mov_b32 m0, s30
	v_mov_b32_e32 v143, v1
	global_load_lds_dwordx4 v144, s[12:13]
	v_mov_b32_e32 v145, v1
	v_lshl_add_u64 v[2:3], s[20:21], 0, v[0:1]
	v_lshl_add_u64 v[4:5], s[20:21], 0, v[146:147]
	v_lshl_add_u64 v[10:11], s[0:1], 0, v[142:143]
	v_lshl_add_u64 v[12:13], s[0:1], 0, v[144:145]
	s_add_i32 m0, s27, 0x18000
	v_lshl_add_u64 v[2:3], v[2:3], 0, s[42:43]
	s_add_i32 s31, s27, 0x8000
	global_load_lds_dwordx4 v[2:3], off
	v_lshl_add_u64 v[2:3], v[4:5], 0, s[42:43]
	s_add_i32 m0, s27, 0x1a000
	s_add_i32 s34, s27, 0xa000
	global_load_lds_dwordx4 v[2:3], off
	v_lshl_add_u64 v[2:3], v[10:11], 0, s[42:43]
	s_mov_b32 m0, s31
	s_nop 0
	global_load_lds_dwordx4 v[2:3], off
	v_lshl_add_u64 v[2:3], v[12:13], 0, s[42:43]
	s_mov_b32 m0, s34
	s_nop 0
	global_load_lds_dwordx4 v[2:3], off
	s_add_i32 m0, s27, 0x1c000
	v_lshl_add_u64 v[2:3], v[6:7], 0, s[42:43]
	global_load_lds_dwordx4 v[2:3], off
	v_lshl_add_u64 v[2:3], v[8:9], 0, s[42:43]
	s_add_i32 m0, s27, 0x1e000
	s_nop 0
	global_load_lds_dwordx4 v[2:3], off
	s_cmp_eq_u32 s3, 1
	s_cselect_b64 s[12:13], -1, 0
	s_cmp_lg_u32 s3, 1
	s_cbranch_scc1 .LBB0_1595
	s_barrier
.LBB0_1595:
	s_waitcnt vmcnt(8)
	s_barrier
	s_and_b32 s35, s2, 3
	s_lshr_b32 s2, s5, 26
	v_bfe_u32 v2, v14, 4, 2
	v_and_b32_e32 v3, 15, v14
	v_lshlrev_b32_e32 v5, 4, v2
	s_add_i32 s2, s4, s2
	v_lshl_or_b32 v160, s3, 6, v3
	v_lshl_or_b32 v3, v3, 6, v5
	v_lshlrev_b32_e32 v5, 2, v14
	s_ashr_i32 s36, s2, 6
	s_lshl_b32 s2, s3, 13
	v_and_b32_e32 v5, 32, v5
	v_bitop3_b32 v6, v3, s2, v5 bitop3:0xde
	s_lshl_b32 s2, s35, 12
	v_readlane_b32 s14, v254, 29
	v_lshlrev_b32_e32 v4, 3, v2
	v_bitop3_b32 v161, v3, s2, v5 bitop3:0xde
	v_cmp_eq_u32_e64 s[2:3], 0, v2
	v_add_u32_e32 v2, v17, v15
	v_readlane_b32 s15, v254, 30
	s_cmp_gt_i32 s4, 63
	v_add_lshl_u32 v2, v2, v16, 1
	v_mov_b32_e32 v3, v1
	v_cndmask_b32_e64 v148, 1.0, 0.5, s[14:15]
	s_waitcnt vmcnt(6)
	s_cselect_b64 s[14:15], -1, 0
	s_add_i32 s37, s36, -2
	v_lshl_add_u64 v[150:151], s[8:9], 0, v[2:3]
	v_add_u32_e32 v2, v20, v18
	s_cmpk_lt_u32 s6, 0x100
	v_add_lshl_u32 v2, v2, v19, 1
	v_lshl_or_b32 v162, s35, 5, v4
	s_cselect_b64 s[16:17], -1, 0
	s_mov_b32 s38, 0
	v_mov_b32_e32 v149, v148
	v_lshl_add_u64 v[152:153], s[8:9], 0, v[2:3]
	v_add_u32_e32 v163, 0, v6
	s_barrier
	s_branch .LBB0_1598

.LBB0_1608:
	v_mov_b32_e32 v125, 0
	s_andn2_b64 vcc, exec, s[14:15]
	v_mov_b32_e32 v124, v125
	v_mov_b32_e32 v123, v125
	v_mov_b32_e32 v122, v125
	v_mov_b32_e32 v129, v125
	v_mov_b32_e32 v128, v125
	v_mov_b32_e32 v127, v125
	v_mov_b32_e32 v126, v125
	v_mov_b32_e32 v113, v125
	v_mov_b32_e32 v112, v125
	v_mov_b32_e32 v111, v125
	v_mov_b32_e32 v110, v125
	v_mov_b32_e32 v109, v125
	v_mov_b32_e32 v108, v125
	v_mov_b32_e32 v107, v125
	v_mov_b32_e32 v106, v125
	v_mov_b32_e32 v97, v125
	v_mov_b32_e32 v96, v125
	v_mov_b32_e32 v95, v125
	v_mov_b32_e32 v94, v125
	v_mov_b32_e32 v93, v125
	v_mov_b32_e32 v92, v125
	v_mov_b32_e32 v91, v125
	v_mov_b32_e32 v90, v125
	v_mov_b32_e32 v81, v125
	v_mov_b32_e32 v80, v125
	v_mov_b32_e32 v79, v125
	v_mov_b32_e32 v78, v125
	v_mov_b32_e32 v77, v125
	v_mov_b32_e32 v76, v125
	v_mov_b32_e32 v75, v125
	v_mov_b32_e32 v74, v125
	v_mov_b32_e32 v121, v125
	v_mov_b32_e32 v120, v125
	v_mov_b32_e32 v119, v125
	v_mov_b32_e32 v118, v125
	v_mov_b32_e32 v117, v125
	v_mov_b32_e32 v116, v125
	v_mov_b32_e32 v115, v125
	v_mov_b32_e32 v114, v125
	v_mov_b32_e32 v105, v125
	v_mov_b32_e32 v104, v125
	v_mov_b32_e32 v103, v125
	v_mov_b32_e32 v102, v125
	v_mov_b32_e32 v101, v125
	v_mov_b32_e32 v100, v125
	v_mov_b32_e32 v99, v125
	v_mov_b32_e32 v98, v125
	s_waitcnt vmcnt(0)
	v_mov_b32_e32 v89, v125
	v_mov_b32_e32 v88, v125
	v_mov_b32_e32 v87, v125
	v_mov_b32_e32 v86, v125
	v_mov_b32_e32 v85, v125
	v_mov_b32_e32 v84, v125
	v_mov_b32_e32 v83, v125
	v_mov_b32_e32 v82, v125
	v_mov_b32_e32 v73, v125
	v_mov_b32_e32 v72, v125
	v_mov_b32_e32 v71, v125
	v_mov_b32_e32 v70, v125
	v_mov_b32_e32 v69, v125
	v_mov_b32_e32 v68, v125
	v_mov_b32_e32 v67, v125
	v_mov_b32_e32 v66, v125
	v_mov_b32_e32 v65, v125
	v_mov_b32_e32 v64, v125
	v_mov_b32_e32 v63, v125
	v_mov_b32_e32 v62, v125
	v_mov_b32_e32 v61, v125
	v_mov_b32_e32 v60, v125
	v_mov_b32_e32 v59, v125
	v_mov_b32_e32 v58, v125
	v_mov_b32_e32 v49, v125
	v_mov_b32_e32 v48, v125
	v_mov_b32_e32 v47, v125
	v_mov_b32_e32 v46, v125
	v_mov_b32_e32 v45, v125
	v_mov_b32_e32 v44, v125
	v_mov_b32_e32 v43, v125
	v_mov_b32_e32 v42, v125
	v_mov_b32_e32 v33, v125
	v_mov_b32_e32 v32, v125
	v_mov_b32_e32 v31, v125
	v_mov_b32_e32 v30, v125
	v_mov_b32_e32 v29, v125
	v_mov_b32_e32 v28, v125
	v_mov_b32_e32 v27, v125
	v_mov_b32_e32 v26, v125
	v_mov_b32_e32 v17, v125
	v_mov_b32_e32 v16, v125
	v_mov_b32_e32 v15, v125
	v_mov_b32_e32 v14, v125
	v_mov_b32_e32 v13, v125
	v_mov_b32_e32 v12, v125
	v_mov_b32_e32 v11, v125
	v_mov_b32_e32 v10, v125
	v_mov_b32_e32 v57, v125
	v_mov_b32_e32 v56, v125
	v_mov_b32_e32 v55, v125
	v_mov_b32_e32 v54, v125
	v_mov_b32_e32 v53, v125
	v_mov_b32_e32 v52, v125
	v_mov_b32_e32 v51, v125
	v_mov_b32_e32 v50, v125
	v_mov_b32_e32 v41, v125
	v_mov_b32_e32 v40, v125
	v_mov_b32_e32 v39, v125
	v_mov_b32_e32 v38, v125
	v_mov_b32_e32 v37, v125
	v_mov_b32_e32 v36, v125
	v_mov_b32_e32 v35, v125
	v_mov_b32_e32 v34, v125
	v_mov_b32_e32 v25, v125
	v_mov_b32_e32 v24, v125
	v_mov_b32_e32 v23, v125
	v_mov_b32_e32 v22, v125
	v_mov_b32_e32 v21, v125
	v_mov_b32_e32 v20, v125
	v_mov_b32_e32 v19, v125
	v_mov_b32_e32 v18, v125
	v_mov_b32_e32 v9, v125
	v_mov_b32_e32 v8, v125
	v_mov_b32_e32 v7, v125
	v_mov_b32_e32 v6, v125
	v_mov_b32_e32 v5, v125
	v_mov_b32_e32 v4, v125
	s_waitcnt lgkmcnt(0)
	v_mov_b32_e32 v3, v125
	v_mov_b32_e32 v2, v125
	s_cbranch_vccnz .LBB0_1612
	s_add_u32 s0, s0, 0x80
	s_addc_u32 s1, s1, 0
	s_add_u32 s44, s20, 0x100
	s_addc_u32 s46, s21, 0
	s_mov_b32 s20, 0

.LBB0_1648:
	v_mov_b32_e32 v125, 0
	s_andn2_b64 vcc, exec, s[12:13]
	v_mov_b32_e32 v124, v125
	v_mov_b32_e32 v123, v125
	v_mov_b32_e32 v122, v125
	v_mov_b32_e32 v117, v125
	v_mov_b32_e32 v116, v125
	v_mov_b32_e32 v115, v125
	v_mov_b32_e32 v114, v125
	v_mov_b32_e32 v109, v125
	v_mov_b32_e32 v108, v125
	v_mov_b32_e32 v107, v125
	v_mov_b32_e32 v106, v125
	v_mov_b32_e32 v101, v125
	v_mov_b32_e32 v100, v125
	v_mov_b32_e32 v99, v125
	v_mov_b32_e32 v98, v125
	v_mov_b32_e32 v93, v125
	v_mov_b32_e32 v92, v125
	v_mov_b32_e32 v91, v125
	v_mov_b32_e32 v90, v125
	s_waitcnt vmcnt(0)
	v_mov_b32_e32 v85, v125
	v_mov_b32_e32 v84, v125
	v_mov_b32_e32 v83, v125
	v_mov_b32_e32 v82, v125
	v_mov_b32_e32 v77, v125
	v_mov_b32_e32 v76, v125
	v_mov_b32_e32 v75, v125
	v_mov_b32_e32 v74, v125
	v_mov_b32_e32 v69, v125
	v_mov_b32_e32 v68, v125
	v_mov_b32_e32 v67, v125
	v_mov_b32_e32 v66, v125
	v_mov_b32_e32 v129, v125
	v_mov_b32_e32 v128, v125
	v_mov_b32_e32 v127, v125
	v_mov_b32_e32 v126, v125
	v_mov_b32_e32 v121, v125
	v_mov_b32_e32 v120, v125
	v_mov_b32_e32 v119, v125
	v_mov_b32_e32 v118, v125
	v_mov_b32_e32 v113, v125
	v_mov_b32_e32 v112, v125
	v_mov_b32_e32 v111, v125
	v_mov_b32_e32 v110, v125
	v_mov_b32_e32 v105, v125
	v_mov_b32_e32 v104, v125
	v_mov_b32_e32 v103, v125
	v_mov_b32_e32 v102, v125
	v_mov_b32_e32 v97, v125
	v_mov_b32_e32 v96, v125
	v_mov_b32_e32 v95, v125
	v_mov_b32_e32 v94, v125
	v_mov_b32_e32 v89, v125
	v_mov_b32_e32 v88, v125
	v_mov_b32_e32 v87, v125
	v_mov_b32_e32 v86, v125
	v_mov_b32_e32 v81, v125
	v_mov_b32_e32 v80, v125
	v_mov_b32_e32 v79, v125
	v_mov_b32_e32 v78, v125
	v_mov_b32_e32 v73, v125
	v_mov_b32_e32 v72, v125
	v_mov_b32_e32 v71, v125
	v_mov_b32_e32 v70, v125
	v_mov_b32_e32 v61, v125
	v_mov_b32_e32 v60, v125
	v_mov_b32_e32 v59, v125
	v_mov_b32_e32 v58, v125
	v_mov_b32_e32 v53, v125
	v_mov_b32_e32 v52, v125
	v_mov_b32_e32 v51, v125
	v_mov_b32_e32 v50, v125
	v_mov_b32_e32 v45, v125
	v_mov_b32_e32 v44, v125
	v_mov_b32_e32 v43, v125
	v_mov_b32_e32 v42, v125
	v_mov_b32_e32 v37, v125
	v_mov_b32_e32 v36, v125
	v_mov_b32_e32 v35, v125
	v_mov_b32_e32 v34, v125
	v_mov_b32_e32 v29, v125
	v_mov_b32_e32 v28, v125
	v_mov_b32_e32 v27, v125
	v_mov_b32_e32 v26, v125
	v_mov_b32_e32 v21, v125
	v_mov_b32_e32 v20, v125
	v_mov_b32_e32 v19, v125
	v_mov_b32_e32 v18, v125
	v_mov_b32_e32 v13, v125
	v_mov_b32_e32 v12, v125
	v_mov_b32_e32 v11, v125
	v_mov_b32_e32 v10, v125
	v_mov_b32_e32 v9, v125
	v_mov_b32_e32 v8, v125
	v_mov_b32_e32 v7, v125
	v_mov_b32_e32 v6, v125
	v_mov_b32_e32 v65, v125
	v_mov_b32_e32 v64, v125
	v_mov_b32_e32 v63, v125
	v_mov_b32_e32 v62, v125
	v_mov_b32_e32 v57, v125
	v_mov_b32_e32 v56, v125
	v_mov_b32_e32 v55, v125
	v_mov_b32_e32 v54, v125
	v_mov_b32_e32 v49, v125
	v_mov_b32_e32 v48, v125
	v_mov_b32_e32 v47, v125
	v_mov_b32_e32 v46, v125
	v_mov_b32_e32 v41, v125
	v_mov_b32_e32 v40, v125
	v_mov_b32_e32 v39, v125
	v_mov_b32_e32 v38, v125
	v_mov_b32_e32 v33, v125
	v_mov_b32_e32 v32, v125
	v_mov_b32_e32 v31, v125
	v_mov_b32_e32 v30, v125
	v_mov_b32_e32 v25, v125
	v_mov_b32_e32 v24, v125
	v_mov_b32_e32 v23, v125
	v_mov_b32_e32 v22, v125
	v_mov_b32_e32 v17, v125
	v_mov_b32_e32 v16, v125
	v_mov_b32_e32 v15, v125
	v_mov_b32_e32 v14, v125
	v_mov_b32_e32 v5, v125
	v_mov_b32_e32 v4, v125
	v_mov_b32_e32 v3, v125
	v_mov_b32_e32 v2, v125
	s_cbranch_vccnz .LBB0_1651
	s_add_u32 s0, s0, 0x80
	s_addc_u32 s1, s1, 0
	s_add_u32 s35, s18, 0x100
	s_addc_u32 s36, s19, 0
	s_mov_b32 s18, 0
